# weight conversion tiles: the 16 loads of a thread issued back to back instead of 16 dependent load/wait/LDS-write rounds (both copies)
# speedup vs baseline: 1.0236x; 1.0236x over previous
; DEV int bid_() { int b = blockIdx.x; asm volatile("" : "+s"(b)); return b; }
; __device__ void phase_wconv(PRef p, int l, float* sm) {
;     ...
;     int first = (bid_() - (g0 % (int)gridDim.x) + (int)gridDim.x) % (int)gridDim.x;
;     for (int t = first; t < nt_total; t += gridDim.x) {
;       int kt = t / nn, nt = t % nn;
;       __syncthreads();
;       for (int e = tid; e < 4096; e += 256) {
;         int i = e >> 6, jj = e & 63;
;         int k = kt * 64 + i, n = nt * 64 + jj;
;         float v = (n < jb.nvalid) ? jb.src[(size_t)k * jb.sld + n] : 0.f;
;         if (jb.rs) v *= jb.rs[k];
;         sm[i * 65 + jj] = v;
;       }
.LBB0_129:
	s_abs_i32 s11, s85
	s_mul_hi_u32 s72, s11, s87
	s_mul_i32 s73, s72, s18
	s_sub_i32 s11, s11, s73
	s_ashr_i32 s10, s85, 31
	s_add_i32 s73, s72, 1
	s_sub_i32 s74, s11, s18
	s_cmp_ge_u32 s11, s18
	s_cselect_b32 s72, s73, s72
	s_cselect_b32 s11, s74, s11
	s_add_i32 s73, s72, 1
	s_cmp_ge_u32 s11, s18
	s_cselect_b32 s11, s73, s72
	s_xor_b32 s11, s11, s10
	s_sub_i32 s88, s11, s10
	s_mul_i32 s10, s88, s18
	s_sub_i32 s89, s85, s10
	s_barrier
	s_and_saveexec_b64 s[72:73], s[4:5]
	s_cbranch_execz .LBB0_136
	v_lshl_or_b32 v12, s89, 6, v4
	v_ashrrev_i32_e32 v13, 31, v12
	s_lshl_b32 s90, s88, 6
	v_cmp_gt_i32_e64 s[10:11], s82, v12
	v_lshl_add_u64 v[12:13], v[12:13], 2, s[64:65]
	s_mov_b64 s[74:75], 0
	v_mov_b32_e32 v16, v2
	s_and_b64 vcc, exec, s[70:71]
	s_cbranch_vccnz .LBB0_132
	v_ashrrev_i32_e32 v20, 6, v2
	v_add_u32_e32 v18, s90, v20
	v_mul_lo_u32 v18, v18, s68
	v_mov_b32_e32 v19, 0
	v_lshl_add_u64 v[18:19], v[18:19], 2, v[12:13]
	s_lshl_b32 s76, s68, 4
	s_mov_b32 s77, 0
	v_mov_b32_e32 v210, 0
	v_mov_b32_e32 v211, 0
	v_mov_b32_e32 v212, 0
	v_mov_b32_e32 v213, 0
	v_mov_b32_e32 v214, 0
	v_mov_b32_e32 v215, 0
	v_mov_b32_e32 v216, 0
	v_mov_b32_e32 v217, 0
	v_mov_b32_e32 v218, 0
	v_mov_b32_e32 v219, 0
	v_mov_b32_e32 v220, 0
	v_mov_b32_e32 v221, 0
	v_mov_b32_e32 v222, 0
	v_mov_b32_e32 v223, 0
	v_mov_b32_e32 v224, 0
	v_mov_b32_e32 v225, 0
	v_mul_u32_u24_e32 v21, 0x104, v20
	v_add_u32_e32 v21, v21, v6
	s_and_saveexec_b64 vcc, s[10:11]
	global_load_dword v210, v[18:19], off
	v_lshl_add_u64 v[18:19], v[18:19], 0, s[76:77]
	global_load_dword v211, v[18:19], off
	v_lshl_add_u64 v[18:19], v[18:19], 0, s[76:77]
	global_load_dword v212, v[18:19], off
	v_lshl_add_u64 v[18:19], v[18:19], 0, s[76:77]
	global_load_dword v213, v[18:19], off
	v_lshl_add_u64 v[18:19], v[18:19], 0, s[76:77]
	global_load_dword v214, v[18:19], off
	v_lshl_add_u64 v[18:19], v[18:19], 0, s[76:77]
	global_load_dword v215, v[18:19], off
	v_lshl_add_u64 v[18:19], v[18:19], 0, s[76:77]
	global_load_dword v216, v[18:19], off
	v_lshl_add_u64 v[18:19], v[18:19], 0, s[76:77]
	global_load_dword v217, v[18:19], off
	v_lshl_add_u64 v[18:19], v[18:19], 0, s[76:77]
	global_load_dword v218, v[18:19], off
	v_lshl_add_u64 v[18:19], v[18:19], 0, s[76:77]
	global_load_dword v219, v[18:19], off
	v_lshl_add_u64 v[18:19], v[18:19], 0, s[76:77]
	global_load_dword v220, v[18:19], off
	v_lshl_add_u64 v[18:19], v[18:19], 0, s[76:77]
	global_load_dword v221, v[18:19], off
	v_lshl_add_u64 v[18:19], v[18:19], 0, s[76:77]
	global_load_dword v222, v[18:19], off
	v_lshl_add_u64 v[18:19], v[18:19], 0, s[76:77]
	global_load_dword v223, v[18:19], off
	v_lshl_add_u64 v[18:19], v[18:19], 0, s[76:77]
	global_load_dword v224, v[18:19], off
	v_lshl_add_u64 v[18:19], v[18:19], 0, s[76:77]
	global_load_dword v225, v[18:19], off
	s_or_b64 exec, exec, vcc
	s_waitcnt vmcnt(0)
	ds_write_b32 v21, v210 offset:0
	ds_write_b32 v21, v211 offset:1040
	ds_write_b32 v21, v212 offset:2080
	ds_write_b32 v21, v213 offset:3120
	ds_write_b32 v21, v214 offset:4160
	ds_write_b32 v21, v215 offset:5200
	ds_write_b32 v21, v216 offset:6240
	ds_write_b32 v21, v217 offset:7280
	ds_write_b32 v21, v218 offset:8320
	ds_write_b32 v21, v219 offset:9360
	ds_write_b32 v21, v220 offset:10400
	ds_write_b32 v21, v221 offset:11440
	ds_write_b32 v21, v222 offset:12480
	ds_write_b32 v21, v223 offset:13520
	ds_write_b32 v21, v224 offset:14560
	ds_write_b32 v21, v225 offset:15600
	s_branch .LBB0_136

; DEV int bid_() { int b = blockIdx.x; asm volatile("" : "+s"(b)); return b; }
; __device__ void phase_wconv(PRef p, int l, float* sm) {
;     ...
;     int first = (bid_() - (g0 % (int)gridDim.x) + (int)gridDim.x) % (int)gridDim.x;
;     for (int t = first; t < nt_total; t += gridDim.x) {
;       int kt = t / nn, nt = t % nn;
;       __syncthreads();
;       for (int e = tid; e < 4096; e += 256) {
;         int i = e >> 6, jj = e & 63;
;         int k = kt * 64 + i, n = nt * 64 + jj;
;         float v = (n < jb.nvalid) ? jb.src[(size_t)k * jb.sld + n] : 0.f;
;         if (jb.rs) v *= jb.rs[k];
;         sm[i * 65 + jj] = v;
;       }
.LBB0_206:
	s_abs_i32 s1, s39
	s_mul_hi_u32 s10, s1, s18
	s_mul_i32 s11, s10, s28
	s_sub_i32 s1, s1, s11
	s_ashr_i32 s0, s39, 31
	s_add_i32 s11, s10, 1
	s_sub_i32 s19, s1, s28
	s_cmp_ge_u32 s1, s28
	s_cselect_b32 s10, s11, s10
	s_cselect_b32 s1, s19, s1
	s_add_i32 s11, s10, 1
	s_cmp_ge_u32 s1, s28
	s_cselect_b32 s1, s11, s10
	s_xor_b32 s1, s1, s0
	s_sub_i32 s0, s1, s0
	s_mul_i32 s1, s0, s28
	s_sub_i32 s1, s39, s1
	s_barrier
	s_and_saveexec_b64 s[62:63], s[4:5]
	s_cbranch_execz .LBB0_213
	v_lshl_or_b32 v10, s1, 6, v4
	v_ashrrev_i32_e32 v11, 31, v10
	s_lshl_b32 s19, s0, 6
	v_cmp_gt_i32_e64 s[10:11], s36, v10
	v_lshl_add_u64 v[10:11], v[10:11], 2, s[14:15]
	s_mov_b64 s[94:95], 0
	v_mov_b32_e32 v15, v0
	s_and_b64 vcc, exec, s[54:55]
	s_cbranch_vccnz .LBB0_209
	v_ashrrev_i32_e32 v20, 6, v0
	v_add_u32_e32 v18, s19, v20
	v_mul_lo_u32 v18, v18, s34
	v_mov_b32_e32 v19, 0
	v_lshl_add_u64 v[18:19], v[18:19], 2, v[10:11]
	s_lshl_b32 s40, s34, 4
	s_mov_b32 s41, 0
	v_mov_b32_e32 v210, 0
	v_mov_b32_e32 v211, 0
	v_mov_b32_e32 v212, 0
	v_mov_b32_e32 v213, 0
	v_mov_b32_e32 v214, 0
	v_mov_b32_e32 v215, 0
	v_mov_b32_e32 v216, 0
	v_mov_b32_e32 v217, 0
	v_mov_b32_e32 v218, 0
	v_mov_b32_e32 v219, 0
	v_mov_b32_e32 v220, 0
	v_mov_b32_e32 v221, 0
	v_mov_b32_e32 v222, 0
	v_mov_b32_e32 v223, 0
	v_mov_b32_e32 v224, 0
	v_mov_b32_e32 v225, 0
	v_mul_u32_u24_e32 v21, 0x104, v20
	v_add_u32_e32 v21, v21, v6
	s_and_saveexec_b64 vcc, s[10:11]
	global_load_dword v210, v[18:19], off
	v_lshl_add_u64 v[18:19], v[18:19], 0, s[40:41]
	global_load_dword v211, v[18:19], off
	v_lshl_add_u64 v[18:19], v[18:19], 0, s[40:41]
	global_load_dword v212, v[18:19], off
	v_lshl_add_u64 v[18:19], v[18:19], 0, s[40:41]
	global_load_dword v213, v[18:19], off
	v_lshl_add_u64 v[18:19], v[18:19], 0, s[40:41]
	global_load_dword v214, v[18:19], off
	v_lshl_add_u64 v[18:19], v[18:19], 0, s[40:41]
	global_load_dword v215, v[18:19], off
	v_lshl_add_u64 v[18:19], v[18:19], 0, s[40:41]
	global_load_dword v216, v[18:19], off
	v_lshl_add_u64 v[18:19], v[18:19], 0, s[40:41]
	global_load_dword v217, v[18:19], off
	v_lshl_add_u64 v[18:19], v[18:19], 0, s[40:41]
	global_load_dword v218, v[18:19], off
	v_lshl_add_u64 v[18:19], v[18:19], 0, s[40:41]
	global_load_dword v219, v[18:19], off
	v_lshl_add_u64 v[18:19], v[18:19], 0, s[40:41]
	global_load_dword v220, v[18:19], off
	v_lshl_add_u64 v[18:19], v[18:19], 0, s[40:41]
	global_load_dword v221, v[18:19], off
	v_lshl_add_u64 v[18:19], v[18:19], 0, s[40:41]
	global_load_dword v222, v[18:19], off
	v_lshl_add_u64 v[18:19], v[18:19], 0, s[40:41]
	global_load_dword v223, v[18:19], off
	v_lshl_add_u64 v[18:19], v[18:19], 0, s[40:41]
	global_load_dword v224, v[18:19], off
	v_lshl_add_u64 v[18:19], v[18:19], 0, s[40:41]
	global_load_dword v225, v[18:19], off
	s_or_b64 exec, exec, vcc
	s_waitcnt vmcnt(0)
	ds_write_b32 v21, v210 offset:0
	ds_write_b32 v21, v211 offset:1040
	ds_write_b32 v21, v212 offset:2080
	ds_write_b32 v21, v213 offset:3120
	ds_write_b32 v21, v214 offset:4160
	ds_write_b32 v21, v215 offset:5200
	ds_write_b32 v21, v216 offset:6240
	ds_write_b32 v21, v217 offset:7280
	ds_write_b32 v21, v218 offset:8320
	ds_write_b32 v21, v219 offset:9360
	ds_write_b32 v21, v220 offset:10400
	ds_write_b32 v21, v221 offset:11440
	ds_write_b32 v21, v222 offset:12480
	ds_write_b32 v21, v223 offset:13520
	ds_write_b32 v21, v224 offset:14560
	ds_write_b32 v21, v225 offset:15600
	s_branch .LBB0_213
